# up-GEMM phase prologue: row-scale partial sums loaded in one batch instead of a load-wait loop
# speedup vs baseline: 1.0000x; 1.0000x over previous
; template <class Epi> __device__ __forceinline__ void run_gemm(const Ctx& C, const bf16_t* A, const bf16_t* Bt, int N, int K, Epi& E, const float* hss, int np) {
;     ...
;         if (hss) { const int row = (C.tid < 256 ? u0.pm : u1.pm) * 256 + (C.tid & 255); const f32x4* p4 = (const f32x4*)(hss + (size_t)row * 64); float s = 0.f;
;             for (int i = 0; i < np / 4; ++i) { const f32x4 q = p4[i]; s += (q[0] + q[1]) + (q[2] + q[3]); }
;             rs = 1.0f / sqrtf(s * (1.0f / DM) + EPS); }
;         RS[C.tid] = rs;
.LBB0_59:
	global_load_dwordx4 v[4:7], v[0:1], off
	global_load_dwordx4 v[8:11], v[0:1], off offset:16
	global_load_dwordx4 v[12:15], v[0:1], off offset:32
	global_load_dwordx4 v[16:19], v[0:1], off offset:48
	global_load_dwordx4 v[20:23], v[0:1], off offset:64
	global_load_dwordx4 v[24:27], v[0:1], off offset:80
	global_load_dwordx4 v[28:31], v[0:1], off offset:96
	global_load_dwordx4 v[32:35], v[0:1], off offset:112
	global_load_dwordx4 v[100:103], v[0:1], off offset:128
	global_load_dwordx4 v[104:107], v[0:1], off offset:144
	global_load_dwordx4 v[108:111], v[0:1], off offset:160
	global_load_dwordx4 v[112:115], v[0:1], off offset:176
	global_load_dwordx4 v[116:119], v[0:1], off offset:192
	global_load_dwordx4 v[120:123], v[0:1], off offset:208
	global_load_dwordx4 v[124:127], v[0:1], off offset:224
	global_load_dwordx4 v[128:131], v[0:1], off offset:240
	s_waitcnt vmcnt(0)
	v_add_f32_e32 v3, v5, v4
	v_add_f32_e32 v36, v6, v7
	v_add_f32_e32 v3, v3, v36
	v_add_f32_e32 v2, v2, v3
	v_add_f32_e32 v3, v9, v8
	v_add_f32_e32 v36, v10, v11
	v_add_f32_e32 v3, v3, v36
	v_add_f32_e32 v2, v2, v3
	v_add_f32_e32 v3, v13, v12
	v_add_f32_e32 v36, v14, v15
	v_add_f32_e32 v3, v3, v36
	v_add_f32_e32 v2, v2, v3
	v_add_f32_e32 v3, v17, v16
	v_add_f32_e32 v36, v18, v19
	v_add_f32_e32 v3, v3, v36
	v_add_f32_e32 v2, v2, v3
	v_add_f32_e32 v3, v21, v20
	v_add_f32_e32 v36, v22, v23
	v_add_f32_e32 v3, v3, v36
	v_add_f32_e32 v2, v2, v3
	v_add_f32_e32 v3, v25, v24
	v_add_f32_e32 v36, v26, v27
	v_add_f32_e32 v3, v3, v36
	v_add_f32_e32 v2, v2, v3
	v_add_f32_e32 v3, v29, v28
	v_add_f32_e32 v36, v30, v31
	v_add_f32_e32 v3, v3, v36
	v_add_f32_e32 v2, v2, v3
	v_add_f32_e32 v3, v33, v32
	v_add_f32_e32 v36, v34, v35
	v_add_f32_e32 v3, v3, v36
	v_add_f32_e32 v2, v2, v3
	v_mov_b32_e32 v37, v2
	v_add_f32_e32 v3, v101, v100
	v_add_f32_e32 v36, v102, v103
	v_add_f32_e32 v3, v3, v36
	v_add_f32_e32 v2, v2, v3
	v_add_f32_e32 v3, v105, v104
	v_add_f32_e32 v36, v106, v107
	v_add_f32_e32 v3, v3, v36
	v_add_f32_e32 v2, v2, v3
	v_add_f32_e32 v3, v109, v108
	v_add_f32_e32 v36, v110, v111
	v_add_f32_e32 v3, v3, v36
	v_add_f32_e32 v2, v2, v3
	v_add_f32_e32 v3, v113, v112
	v_add_f32_e32 v36, v114, v115
	v_add_f32_e32 v3, v3, v36
	v_add_f32_e32 v2, v2, v3
	v_add_f32_e32 v3, v117, v116
	v_add_f32_e32 v36, v118, v119
	v_add_f32_e32 v3, v3, v36
	v_add_f32_e32 v2, v2, v3
	v_add_f32_e32 v3, v121, v120
	v_add_f32_e32 v36, v122, v123
	v_add_f32_e32 v3, v3, v36
	v_add_f32_e32 v2, v2, v3
	v_add_f32_e32 v3, v125, v124
	v_add_f32_e32 v36, v126, v127
	v_add_f32_e32 v3, v3, v36
	v_add_f32_e32 v2, v2, v3
	v_add_f32_e32 v3, v129, v128
	v_add_f32_e32 v36, v130, v131
	v_add_f32_e32 v3, v3, v36
	v_add_f32_e32 v2, v2, v3
	s_cmp_eq_u32 s0, 8
	s_cselect_b64 vcc, -1, 0
	s_nop 1
	v_cndmask_b32_e32 v2, v2, v37, vcc
	v_fmamk_f32 v0, v2, 0x3a000000, v238
	s_mov_b32 s0, 0xf800000
	v_mul_f32_e32 v1, 0x4f800000, v0
	v_cmp_gt_f32_e32 vcc, s0, v0
	v_readfirstlane_b32 s27, v250
	s_nop 0
	v_cndmask_b32_e32 v0, v0, v1, vcc
	v_sqrt_f32_e32 v1, v0
	s_nop 0
	v_add_u32_e32 v2, -1, v1
	v_fma_f32 v4, -v2, v1, v0
	v_add_u32_e32 v3, 1, v1
	v_cmp_ge_f32_e64 s[0:1], 0, v4
	s_nop 1
	v_cndmask_b32_e64 v2, v1, v2, s[0:1]
	v_fma_f32 v1, -v3, v1, v0
	v_cmp_lt_f32_e64 s[0:1], 0, v1
	s_nop 1
	v_cndmask_b32_e64 v1, v2, v3, s[0:1]
	v_mul_f32_e32 v2, 0x37800000, v1
	v_cndmask_b32_e32 v1, v1, v2, vcc
	v_cmp_class_f32_e32 vcc, v0, v239
	s_nop 1
	v_cndmask_b32_e32 v0, v1, v0, vcc
	v_div_scale_f32 v1, s[0:1], v0, v0, 1.0
	v_rcp_f32_e32 v2, v1
	v_readlane_b32 s0, v252, 36
	v_readlane_b32 s1, v252, 37
	v_fma_f32 v3, -v1, v2, 1.0
	v_fmac_f32_e32 v2, v3, v2
	v_div_scale_f32 v3, vcc, 1.0, v0, 1.0
	v_mul_f32_e32 v4, v3, v2
	v_fma_f32 v5, -v1, v4, v3
	v_fmac_f32_e32 v4, v5, v2
	v_fma_f32 v1, -v1, v4, v3
	v_div_fmas_f32 v1, v1, v2, v4
	v_div_fixup_f32 v0, v1, v0, 1.0
	v_lshl_add_u32 v1, v250, 2, 0
	v_add_u32_e32 v1, 0x22100, v1
	s_and_b64 vcc, exec, s[0:1]
	ds_write_b32 v1, v0
	s_waitcnt lgkmcnt(0)
	s_barrier
	s_cbranch_vccz .LBB0_92
; #define PG8_STAGE(bufoff, gbase, voff) do { _Pragma("unroll") for (int _i = 0; _i < 2; ++_i) \
;         __builtin_amdgcn_global_load_lds((const unsigned*)((const char*)(gbase) + (voff)[_i]), (PG8_LAS unsigned*)(lds + (bufoff) + ldsw + _i * 8192), 16, 0, 0); } while (0)
; template <class Epi, class Sched, bool ALIGN_EPI = false, bool SP2 = false>
; __device__ __forceinline__ void gemm_phase(PG8_LAS unsigned char* lds, const Gemm g, const Sched& S, const Epi& E, const int tid_in) {
;     ...
;     for (int i = 0; i < 2; ++i) { int R, C; stage_rc(tid * 16 + i * 8192, R, C); const int Rb = Epi::PERM ? ((R & ~31) + perm32(R & 31)) : R;
;         const int Ra = Epi::APERM ? (8 * (16 * ((R >> 6) & 1) + (R & 15)) + ((R >> 4) & 3)) : R; voffA[i] = (unsigned)(Ra * K + C) * 2u; voffB[i] = (unsigned)(Rb * K + C) * 2u; }
;     const size_t kstep = (size_t)(BK * 2);
;     const size_t hstep = (size_t)HALF * K * 2;
;     const size_t tstep = 2 * hstep;
;     const size_t hstepA = Epi::APERM ? (size_t)4 * K * 2 : hstep;
;     const unsigned ldsw = (unsigned)wid * 1024u;
;     const int aoff = lds_byte(wr * 64 + fr, fq * 8), boff = lds_byte(wc * 32 + fr, fq * 8);
;     ...
;     Unit cur, nxt; int ui = 0;
;     if (!S.next(0, cur)) return;
;     f32x4 acc[2][2][4][2];
; #pragma unroll
;     for (int a = 0; a < 2; ++a)
; #pragma unroll
;         for (int b = 0; b < 2; ++b)
; #pragma unroll
;             for (int m = 0; m < 4; ++m)
; #pragma unroll
;                 for (int n = 0; n < 2; ++n) acc[a][b][m][n] = (f32x4){0.f, 0.f, 0.f, 0.f};
;     bf16x8 At[4][2], B0[2][2], B1[2][2];
;     const char* cA = (const char*)g.A + (size_t)cur.pm * tstep; const char* cB = (const char*)g.Bt + (size_t)cur.pn * tstep;
;     S.a_ready(cur);
;     if constexpr (SP2) {
;         PG8_STAGE(PG8_SB(0, 0), cB, voffB); PG8_STAGE(PG8_SB(0, 1), cB + hstep, voffB); PG8_STAGE(PG8_SA(0, 0), cA, voffA); PG8_STAGE(PG8_SA(0, 1), cA + hstepA, voffA);
;         if (wr == 1) PG8_BAR;
;         PG8_WAIT_V(2); PG8_BAR;
;         PG8_STAGE(PG8_SB(1, 0), cB + kstep, voffB); PG8_STAGE(PG8_SA(1, 0), cA + kstep, voffA); PG8_STAGE(PG8_SB(1, 1), cB + hstep + kstep, voffB);
;         PG8_WAIT_V(6); PG8_BAR;
;     } else {
;         PG8_STAGE(PG8_SB(0, 0), cB, voffB); PG8_STAGE(PG8_SA(0, 0), cA, voffA); PG8_STAGE(PG8_SB(0, 1), cB + hstep, voffB); PG8_STAGE(PG8_SA(0, 1), cA + hstepA, voffA);
;         if (wr == 1) PG8_BAR;
	v_lshlrev_b32_e32 v0, 4, v250
	v_add_u32_e32 v1, 0x2000, v0
	v_ashrrev_i32_e32 v2, 31, v1
	v_lshrrev_b32_e32 v2, 22, v2
	v_add_u32_e32 v2, v1, v2
	v_ashrrev_i32_e32 v2, 10, v2
	v_mul_i32_i24_e32 v3, 0x400, v2
	v_sub_u32_e32 v1, v1, v3
	v_lshrrev_b32_e32 v3, 4, v1
	v_bitop3_b32 v1, v3, v1, 32 bitop3:0x6c
	v_ashrrev_i32_e32 v3, 31, v1
	v_lshrrev_b32_e32 v3, 26, v3
	s_ashr_i32 s42, s27, 6
	v_readlane_b32 s1, v255, 14
	v_add_u32_e32 v3, v1, v3
	v_lshlrev_b32_e32 v4, 3, v2
	s_ashr_i32 s26, s27, 8
	s_lshl_b32 s96, s42, 10
	s_mul_hi_i32 s0, s1, 0x2c00000
	s_mul_i32 s1, s1, 0x2c00000
	v_readlane_b32 s22, v252, 32
	v_ashrrev_i32_e32 v6, 6, v3
	v_and_b32_e32 v4, -16, v4
	v_and_b32_e32 v3, 0xc0, v3
	v_readlane_b32 s23, v252, 33
	s_add_u32 s22, s22, s1
	v_add_u32_e32 v4, v6, v4
	v_lshlrev_b32_e32 v2, 5, v2
	v_sub_u32_e32 v1, v1, v3
	s_addc_u32 s23, s23, s0
	v_and_b32_e32 v5, 3, v6
	s_mov_b32 s0, 0xfffe0
	v_lshrrev_b32_e32 v7, 2, v4
	v_lshlrev_b32_e32 v9, 1, v4
	v_and_b32_e32 v2, 32, v2
	v_ashrrev_i16_sdwa v1, v241, sext(v1) dst_sel:DWORD dst_unused:UNUSED_PAD src0_sel:DWORD src1_sel:BYTE_0
	v_and_or_b32 v5, v4, s0, v5
	v_and_b32_e32 v8, 4, v7
	v_and_b32_e32 v9, 24, v9
	v_add_u32_sdwa v1, v2, sext(v1) dst_sel:DWORD dst_unused:UNUSED_PAD src0_sel:DWORD src1_sel:WORD_0
	v_or3_b32 v5, v5, v8, v9
	v_lshlrev_b32_e32 v2, 1, v1
	v_lshl_add_u32 v174, v5, 12, v2
	v_lshlrev_b32_e32 v2, 7, v4
	v_and_b32_e32 v2, 0x1800, v2
	v_and_b32_e32 v6, 15, v6
	v_add_lshl_u32 v5, v1, v2, 1
	v_and_or_b32 v1, v7, 16, v6
	v_lshl_add_u32 v176, v1, 15, v5
	v_bfe_i32 v1, v250, 27, 1
	v_lshrrev_b32_e32 v1, 22, v1
	v_add_u32_e32 v1, v0, v1
	v_and_b32_e32 v1, 0xfffffc00, v1
	v_sub_u32_e32 v0, v0, v1
	v_lshrrev_b32_e32 v1, 4, v0
	v_ashrrev_i32_e32 v3, 31, v250
	v_bitop3_b32 v0, v1, v0, 32 bitop3:0x6c
	v_lshrrev_b32_e32 v3, 26, v3
	v_ashrrev_i32_e32 v1, 31, v0
	v_add_u32_e32 v3, v250, v3
	v_lshrrev_b32_e32 v1, 26, v1
	v_ashrrev_i32_e32 v3, 6, v3
	v_add_u32_e32 v1, v0, v1
	v_lshlrev_b32_e32 v7, 3, v3
	v_ashrrev_i32_e32 v2, 6, v1
	v_and_b32_e32 v7, -16, v7
	v_add_u32_e32 v7, v2, v7
	v_and_b32_e32 v1, 0xc0, v1
	v_and_b32_e32 v8, 3, v2
	v_lshrrev_b32_e32 v12, 2, v7
	v_lshlrev_b32_e32 v10, 1, v7
	v_sub_u32_e32 v0, v0, v1
	v_and_or_b32 v8, v7, s0, v8
	v_and_b32_e32 v9, 4, v12
	v_and_b32_e32 v10, 24, v10
	v_lshlrev_b32_e32 v3, 5, v3
	v_ashrrev_i16_sdwa v0, v241, sext(v0) dst_sel:DWORD dst_unused:UNUSED_PAD src0_sel:DWORD src1_sel:BYTE_0
	v_or3_b32 v10, v8, v9, v10
	v_and_b32_e32 v8, 32, v3
	v_bfe_i32 v9, v0, 0, 16
	v_readlane_b32 s0, v253, 33
	v_add_u32_e32 v0, v8, v9
	v_readlane_b32 s1, v253, 34
	v_writelane_b32 v255, s22, 22
	s_add_u32 s22, s22, s0
	v_lshlrev_b32_e32 v1, 1, v0
	v_writelane_b32 v255, s23, 18
	s_addc_u32 s23, s23, s1
	s_add_i32 s56, s96, 0
	v_lshl_add_u32 v178, v10, 12, v1
	s_add_i32 m0, s56, 0x10000
	v_lshlrev_b32_e32 v1, 7, v7
	global_load_lds_dwordx4 v178, s[22:23]
	s_add_i32 m0, s56, 0x12000
	s_add_u32 s0, s22, 0x80000
	v_and_b32_e32 v11, 15, v2
	global_load_lds_dwordx4 v174, s[22:23]
	s_addc_u32 s1, s23, 0
	s_add_i32 m0, s56, 0x14000
	v_and_b32_e32 v10, 0x1800, v1
	v_and_or_b32 v1, v12, 16, v11
	global_load_lds_dwordx4 v178, s[0:1]
	s_add_i32 m0, s56, 0x16000
	v_add_u32_e32 v0, v0, v10
	v_lshlrev_b32_e32 v1, 15, v1
	global_load_lds_dwordx4 v174, s[0:1]
	v_readlane_b32 s0, v253, 35
	v_lshl_add_u32 v180, v0, 1, v1
	s_mov_b32 m0, s56
	v_readlane_b32 s1, v253, 36
	s_add_i32 s57, s56, 0x2000
	v_readlane_b32 s44, v253, 37
	v_readlane_b32 s45, v253, 38
	v_mov_b32_e32 v179, v65
	v_mov_b32_e32 v175, v65
	global_load_lds_dwordx4 v180, s[0:1]
	s_mov_b32 m0, s57
	v_lshl_add_u64 v[0:1], s[22:23], 0, v[178:179]
	global_load_lds_dwordx4 v176, s[0:1]
	s_add_i32 s0, s56, 0x4000
	s_mov_b32 m0, s0
	s_add_i32 s1, s56, 0x6000
	global_load_lds_dwordx4 v180, s[44:45]
	s_mov_b32 m0, s1
	s_cmp_eq_u32 s26, 1
	global_load_lds_dwordx4 v176, s[44:45]
	s_cselect_b64 s[44:45], -1, 0
	v_writelane_b32 v255, s44, 20
	s_cmp_lg_u32 s26, 1
	v_lshl_add_u64 v[2:3], s[22:23], 0, v[174:175]
	v_writelane_b32 v255, s45, 21
	s_cbranch_scc1 .LBB0_63
	s_barrier
